# P6 epilogue: row sum of squares reduced directly from the prefetch buffer (same association), no register copies
# baseline (speedup 1.0000x reference)
; #define GAS __attribute__((address_space(1)))
; __device__ __forceinline__ unsigned cvt_pk_bf16(float lo, float hi) { f32x2 v = {lo, hi}; bf16x2_t b = __builtin_convertvector(v, bf16x2_t); return __builtin_bit_cast(unsigned, b); }
; __device__ __forceinline__ float sigmoid_f(float x) { return __builtin_amdgcn_rcpf(1.0f + __builtin_amdgcn_exp2f(-x * LOG2E)); }
; __device__ __forceinline__ float row_rs(const GAS float* rowss, int row) {
;     const GAS f32x4* p = (const GAS f32x4*)(rowss + (size_t)row * 16); const f32x4 a = p[0], b = p[1], c = p[2], d = p[3];
;     const float s = ((a[0] + a[1]) + (a[2] + a[3])) + ((b[0] + b[1]) + (b[2] + b[3])) + ((c[0] + c[1]) + (c[2] + c[3])) + ((d[0] + d[1]) + (d[2] + d[3]));
;     return __builtin_amdgcn_rsqf(s * (1.0f / 1024.0f) + 1e-6f);
;     __device__ __forceinline__ void operator()(const f32x4 (&acc)[2][2][4][2], const Unit& u, int wr, int wc, int fr, int fq) const {
;     ...
;             for (int m = 0; m < 4; ++m) { const int row = row0 + ai * HALF + m * 16; const float rs = row_rs(rowss, row); GAS bf16_t* rowp = H + (size_t)row * 2816 + col0;
; #pragma unroll
;                 for (int bj = 0; bj < 2; ++bj) { const f32x4 g = acc[ai][bj][m][0] * rs, uu = acc[ai][bj][m][1] * rs;
;                     u32x2 w; w.x = cvt_pk_bf16(g[0] * sigmoid_f(g[0]) * uu[0], g[1] * sigmoid_f(g[1]) * uu[1]); w.y = cvt_pk_bf16(g[2] * sigmoid_f(g[2]) * uu[2], g[3] * sigmoid_f(g[3]) * uu[3]);
;                     *(GAS u32x2*)(rowp + bj * (HALF / 2)) = w; } }
.LBB0_755:
	v_lshl_add_u32 v144, s18, 8, v146
	v_lshl_or_b32 v140, s19, 8, v148
	v_ashrrev_i32_e32 v145, 31, v144
	v_ashrrev_i32_e32 v162, 1, v140
	v_lshlrev_b64 v[140:141], 6, v[144:145]
	v_lshl_add_u64 v[158:159], s[4:5], 0, v[140:141]
	s_nop 0
	v_ashrrev_i32_e32 v163, 31, v162
	s_movk_i32 s11, 0x1600
	s_andn2_b64 vcc, exec, s[6:7]
	v_mov_b32_e32 v224, v140
	global_load_dwordx4 v[192:195], v224, s[4:5]
	global_load_dwordx4 v[196:199], v224, s[4:5] offset:16
	global_load_dwordx4 v[200:203], v224, s[4:5] offset:32
	global_load_dwordx4 v[204:207], v224, s[4:5] offset:48
	v_add_u32_e32 v225, 0x400, v224
	global_load_dwordx4 v[208:211], v225, s[4:5]
	global_load_dwordx4 v[212:215], v225, s[4:5] offset:16
	global_load_dwordx4 v[216:219], v225, s[4:5] offset:32
	global_load_dwordx4 v[220:223], v225, s[4:5] offset:48
	s_waitcnt vmcnt(4)
	v_add_f32_e32 v226, v192, v193
	v_add_f32_e32 v227, v194, v195
	v_add_f32_e32 v228, v226, v227
	v_add_f32_e32 v226, v196, v197
	v_add_f32_e32 v227, v198, v199
	v_add_f32_e32 v229, v226, v227
	v_add_f32_e32 v228, v228, v229
	v_add_f32_e32 v226, v200, v201
	v_add_f32_e32 v227, v202, v203
	v_add_f32_e32 v229, v226, v227
	v_add_f32_e32 v228, v228, v229
	v_add_f32_e32 v226, v204, v205
	v_add_f32_e32 v227, v206, v207
	v_add_f32_e32 v229, v226, v227
	v_add_f32_e32 v228, v228, v229
	v_mov_b32_e32 v140, v228
	v_lshlrev_b64 v[142:143], 1, v[162:163]
	v_fmamk_f32 v140, v140, 0x3a800000, v234
	v_rsq_f32_e32 v150, v140
	v_mov_b64_e32 v[140:141], s[2:3]
	v_mad_i64_i32 v[152:153], s[18:19], v144, s11, v[140:141]
	v_pk_mul_f32 v[126:127], v[126:127], v[150:151] op_sel_hi:[1,0]
	v_pk_mul_f32 v[122:123], v[122:123], v[150:151] op_sel_hi:[1,0]
	v_mul_f32_e32 v145, 0xbfb8aa3b, v126
	v_exp_f32_e32 v145, v145
	v_pk_mul_f32 v[128:129], v[128:129], v[150:151] op_sel_hi:[1,0]
	v_pk_mul_f32 v[124:125], v[124:125], v[150:151] op_sel_hi:[1,0]
	v_lshl_add_u64 v[152:153], v[152:153], 0, v[142:143]
	v_add_f32_e32 v145, 1.0, v145
	v_rcp_f32_e32 v154, v145
	v_mul_f32_e32 v145, 0xbfb8aa3b, v127
	v_exp_f32_e32 v145, v145
	v_pk_mul_f32 v[118:119], v[118:119], v[150:151] op_sel_hi:[1,0]
	v_pk_mul_f32 v[114:115], v[114:115], v[150:151] op_sel_hi:[1,0]
	v_pk_mul_f32 v[120:121], v[120:121], v[150:151] op_sel_hi:[1,0]
	v_add_f32_e32 v145, 1.0, v145
	v_rcp_f32_e32 v155, v145
	v_pk_mul_f32 v[116:117], v[116:117], v[150:151] op_sel_hi:[1,0]
	v_pk_mul_f32 v[126:127], v[126:127], v[154:155]
	s_nop 0
	v_pk_mul_f32 v[122:123], v[122:123], v[126:127]
	s_nop 0
	v_cvt_pk_bf16_f32 v122, v122, v123
	v_mul_f32_e32 v123, 0xbfb8aa3b, v128
	v_exp_f32_e32 v123, v123
	s_nop 0
	v_add_f32_e32 v123, 1.0, v123
	v_rcp_f32_e32 v126, v123
	v_mul_f32_e32 v123, 0xbfb8aa3b, v129
	v_exp_f32_e32 v123, v123
	s_nop 0
	v_add_f32_e32 v123, 1.0, v123
	v_rcp_f32_e32 v127, v123
	s_nop 0
	v_pk_mul_f32 v[126:127], v[128:129], v[126:127]
	s_nop 0
	v_pk_mul_f32 v[124:125], v[124:125], v[126:127]
	s_nop 0
	v_cvt_pk_bf16_f32 v123, v124, v125
	global_store_dwordx2 v[152:153], v[122:123], off
	v_mul_f32_e32 v122, 0xbfb8aa3b, v118
	v_mul_f32_e32 v123, 0xbfb8aa3b, v119
	v_exp_f32_e32 v122, v122
	v_exp_f32_e32 v123, v123
	v_add_f32_e32 v122, 1.0, v122
	v_add_f32_e32 v123, 1.0, v123
	v_rcp_f32_e32 v122, v122
	v_rcp_f32_e32 v123, v123
	s_nop 0
	v_pk_mul_f32 v[118:119], v[118:119], v[122:123]
	s_nop 0
	v_pk_mul_f32 v[114:115], v[114:115], v[118:119]
	s_nop 0
	v_cvt_pk_bf16_f32 v114, v114, v115
	v_mul_f32_e32 v115, 0xbfb8aa3b, v120
	v_exp_f32_e32 v115, v115
	s_nop 0
	v_add_f32_e32 v115, 1.0, v115
	v_rcp_f32_e32 v118, v115
	v_mul_f32_e32 v115, 0xbfb8aa3b, v121
	v_exp_f32_e32 v115, v115
	s_nop 0
	v_add_f32_e32 v115, 1.0, v115
	v_rcp_f32_e32 v119, v115
	s_nop 0
	v_pk_mul_f32 v[118:119], v[120:121], v[118:119]
	s_nop 0
	v_pk_mul_f32 v[116:117], v[116:117], v[118:119]
	s_nop 0
	v_cvt_pk_bf16_f32 v115, v116, v117
	global_store_dwordx2 v[152:153], v[114:115], off offset:128
	v_or_b32_e32 v114, 16, v144
	v_ashrrev_i32_e32 v115, 31, v114
	v_lshlrev_b64 v[116:117], 6, v[114:115]
	v_lshl_add_u64 v[128:129], s[4:5], 0, v[116:117]
	v_add_u32_e32 v225, 0x800, v224
	global_load_dwordx4 v[192:195], v225, s[4:5]
	global_load_dwordx4 v[196:199], v225, s[4:5] offset:16
	global_load_dwordx4 v[200:203], v225, s[4:5] offset:32
	global_load_dwordx4 v[204:207], v225, s[4:5] offset:48
	s_waitcnt vmcnt(4)
; #define GAS __attribute__((address_space(1)))
; __device__ __forceinline__ unsigned cvt_pk_bf16(float lo, float hi) { f32x2 v = {lo, hi}; bf16x2_t b = __builtin_convertvector(v, bf16x2_t); return __builtin_bit_cast(unsigned, b); }
; __device__ __forceinline__ float sigmoid_f(float x) { return __builtin_amdgcn_rcpf(1.0f + __builtin_amdgcn_exp2f(-x * LOG2E)); }
; __device__ __forceinline__ float row_rs(const GAS float* rowss, int row) {
;     const GAS f32x4* p = (const GAS f32x4*)(rowss + (size_t)row * 16); const f32x4 a = p[0], b = p[1], c = p[2], d = p[3];
;     const float s = ((a[0] + a[1]) + (a[2] + a[3])) + ((b[0] + b[1]) + (b[2] + b[3])) + ((c[0] + c[1]) + (c[2] + c[3])) + ((d[0] + d[1]) + (d[2] + d[3]));
;     return __builtin_amdgcn_rsqf(s * (1.0f / 1024.0f) + 1e-6f);
;     __device__ __forceinline__ void operator()(const f32x4 (&acc)[2][2][4][2], const Unit& u, int wr, int wc, int fr, int fq) const {
;     ...
;             for (int m = 0; m < 4; ++m) { const int row = row0 + ai * HALF + m * 16; const float rs = row_rs(rowss, row); GAS bf16_t* rowp = H + (size_t)row * 2816 + col0;
; #pragma unroll
;                 for (int bj = 0; bj < 2; ++bj) { const f32x4 g = acc[ai][bj][m][0] * rs, uu = acc[ai][bj][m][1] * rs;
;                     u32x2 w; w.x = cvt_pk_bf16(g[0] * sigmoid_f(g[0]) * uu[0], g[1] * sigmoid_f(g[1]) * uu[1]); w.y = cvt_pk_bf16(g[2] * sigmoid_f(g[2]) * uu[2], g[3] * sigmoid_f(g[3]) * uu[3]);
;                     *(GAS u32x2*)(rowp + bj * (HALF / 2)) = w; } }
	v_add_f32_e32 v226, v208, v209
	v_add_f32_e32 v227, v210, v211
	v_add_f32_e32 v228, v226, v227
	v_add_f32_e32 v226, v212, v213
	v_add_f32_e32 v227, v214, v215
	v_add_f32_e32 v229, v226, v227
	v_add_f32_e32 v228, v228, v229
	v_add_f32_e32 v226, v216, v217
	v_add_f32_e32 v227, v218, v219
	v_add_f32_e32 v229, v226, v227
	v_add_f32_e32 v228, v228, v229
	v_add_f32_e32 v226, v220, v221
	v_add_f32_e32 v227, v222, v223
	v_add_f32_e32 v229, v226, v227
	v_add_f32_e32 v228, v228, v229
	v_mov_b32_e32 v115, v228
	v_fmamk_f32 v115, v115, 0x3a800000, v234
	v_rsq_f32_e32 v116, v115
	v_mad_i64_i32 v[114:115], s[18:19], v114, s11, v[140:141]
	v_lshl_add_u64 v[114:115], v[114:115], 0, v[142:143]
	v_pk_mul_f32 v[110:111], v[110:111], v[116:117] op_sel_hi:[1,0]
	v_pk_mul_f32 v[112:113], v[112:113], v[116:117] op_sel_hi:[1,0]
	v_pk_mul_f32 v[108:109], v[108:109], v[116:117] op_sel_hi:[1,0]
	v_pk_mul_f32 v[106:107], v[106:107], v[116:117] op_sel_hi:[1,0]
	v_mul_f32_e32 v117, 0xbfb8aa3b, v110
	v_exp_f32_e32 v117, v117
	s_nop 0
	v_add_f32_e32 v117, 1.0, v117
	v_rcp_f32_e32 v118, v117
	v_mul_f32_e32 v117, 0xbfb8aa3b, v111
	v_exp_f32_e32 v117, v117
	s_nop 0
	v_add_f32_e32 v117, 1.0, v117
	v_rcp_f32_e32 v119, v117
	v_pk_mul_f32 v[102:103], v[102:103], v[116:117] op_sel_hi:[1,0]
	v_pk_mul_f32 v[98:99], v[98:99], v[116:117] op_sel_hi:[1,0]
	v_pk_mul_f32 v[104:105], v[104:105], v[116:117] op_sel_hi:[1,0]
	v_pk_mul_f32 v[110:111], v[110:111], v[118:119]
	v_pk_mul_f32 v[100:101], v[100:101], v[116:117] op_sel_hi:[1,0]
	v_pk_mul_f32 v[106:107], v[106:107], v[110:111]
	s_nop 0
	v_cvt_pk_bf16_f32 v106, v106, v107
	v_mul_f32_e32 v107, 0xbfb8aa3b, v112
	v_exp_f32_e32 v107, v107
	s_nop 0
	v_add_f32_e32 v107, 1.0, v107
	v_rcp_f32_e32 v110, v107
	v_mul_f32_e32 v107, 0xbfb8aa3b, v113
	v_exp_f32_e32 v107, v107
	s_nop 0
	v_add_f32_e32 v107, 1.0, v107
	v_rcp_f32_e32 v111, v107
	s_nop 0
	v_pk_mul_f32 v[110:111], v[112:113], v[110:111]
	s_nop 0
	v_pk_mul_f32 v[108:109], v[108:109], v[110:111]
	s_nop 0
	v_cvt_pk_bf16_f32 v107, v108, v109
	global_store_dwordx2 v[114:115], v[106:107], off
	v_mul_f32_e32 v106, 0xbfb8aa3b, v102
	v_mul_f32_e32 v107, 0xbfb8aa3b, v103
	v_exp_f32_e32 v106, v106
	v_exp_f32_e32 v107, v107
	v_add_f32_e32 v106, 1.0, v106
	v_add_f32_e32 v107, 1.0, v107
	v_rcp_f32_e32 v106, v106
	v_rcp_f32_e32 v107, v107
	s_nop 0
	v_pk_mul_f32 v[102:103], v[102:103], v[106:107]
	s_nop 0
	v_pk_mul_f32 v[98:99], v[98:99], v[102:103]
	s_nop 0
	v_cvt_pk_bf16_f32 v98, v98, v99
	v_mul_f32_e32 v99, 0xbfb8aa3b, v104
	v_exp_f32_e32 v99, v99
	s_nop 0
	v_add_f32_e32 v99, 1.0, v99
	v_rcp_f32_e32 v102, v99
	v_mul_f32_e32 v99, 0xbfb8aa3b, v105
	v_exp_f32_e32 v99, v99
	s_nop 0
	v_add_f32_e32 v99, 1.0, v99
	v_rcp_f32_e32 v103, v99
	s_nop 0
	v_pk_mul_f32 v[102:103], v[104:105], v[102:103]
	s_nop 0
	v_pk_mul_f32 v[100:101], v[100:101], v[102:103]
	s_nop 0
	v_cvt_pk_bf16_f32 v99, v100, v101
	global_store_dwordx2 v[114:115], v[98:99], off offset:128
	v_or_b32_e32 v98, 32, v144
	v_ashrrev_i32_e32 v99, 31, v98
	v_lshlrev_b64 v[100:101], 6, v[98:99]
	v_lshl_add_u64 v[112:113], s[4:5], 0, v[100:101]
	s_nop 0
	v_add_u32_e32 v225, 0xc00, v224
	global_load_dwordx4 v[208:211], v225, s[4:5]
	global_load_dwordx4 v[212:215], v225, s[4:5] offset:16
	global_load_dwordx4 v[216:219], v225, s[4:5] offset:32
	global_load_dwordx4 v[220:223], v225, s[4:5] offset:48
	s_waitcnt vmcnt(4)
	v_add_f32_e32 v226, v192, v193
	v_add_f32_e32 v227, v194, v195
	v_add_f32_e32 v228, v226, v227
	v_add_f32_e32 v226, v196, v197
	v_add_f32_e32 v227, v198, v199
	v_add_f32_e32 v229, v226, v227
	v_add_f32_e32 v228, v228, v229
	v_add_f32_e32 v226, v200, v201
	v_add_f32_e32 v227, v202, v203
	v_add_f32_e32 v229, v226, v227
	v_add_f32_e32 v228, v228, v229
	v_add_f32_e32 v226, v204, v205
	v_add_f32_e32 v227, v206, v207
	v_add_f32_e32 v229, v226, v227
	v_add_f32_e32 v228, v228, v229
	v_mov_b32_e32 v99, v228
	v_fmamk_f32 v99, v99, 0x3a800000, v234
	v_rsq_f32_e32 v100, v99
	v_mad_i64_i32 v[98:99], s[18:19], v98, s11, v[140:141]
	v_lshl_add_u64 v[98:99], v[98:99], 0, v[142:143]
	v_pk_mul_f32 v[94:95], v[94:95], v[100:101] op_sel_hi:[1,0]
	v_pk_mul_f32 v[96:97], v[96:97], v[100:101] op_sel_hi:[1,0]
	v_pk_mul_f32 v[92:93], v[92:93], v[100:101] op_sel_hi:[1,0]
	v_pk_mul_f32 v[90:91], v[90:91], v[100:101] op_sel_hi:[1,0]
	v_mul_f32_e32 v101, 0xbfb8aa3b, v94
	v_exp_f32_e32 v101, v101
	s_nop 0
	v_add_f32_e32 v101, 1.0, v101
	v_rcp_f32_e32 v102, v101
	v_mul_f32_e32 v101, 0xbfb8aa3b, v95
	v_exp_f32_e32 v101, v101
	s_nop 0
	v_add_f32_e32 v101, 1.0, v101
	v_rcp_f32_e32 v103, v101
	v_pk_mul_f32 v[86:87], v[86:87], v[100:101] op_sel_hi:[1,0]
	v_pk_mul_f32 v[82:83], v[82:83], v[100:101] op_sel_hi:[1,0]
	v_pk_mul_f32 v[88:89], v[88:89], v[100:101] op_sel_hi:[1,0]
	v_pk_mul_f32 v[94:95], v[94:95], v[102:103]
	v_pk_mul_f32 v[84:85], v[84:85], v[100:101] op_sel_hi:[1,0]
	v_pk_mul_f32 v[90:91], v[90:91], v[94:95]
	s_nop 0
	v_cvt_pk_bf16_f32 v90, v90, v91
	v_mul_f32_e32 v91, 0xbfb8aa3b, v96
	v_exp_f32_e32 v91, v91
	s_nop 0
	v_add_f32_e32 v91, 1.0, v91
	v_rcp_f32_e32 v94, v91
	v_mul_f32_e32 v91, 0xbfb8aa3b, v97
	v_exp_f32_e32 v91, v91
	s_nop 0
	v_add_f32_e32 v91, 1.0, v91
	v_rcp_f32_e32 v95, v91
	s_nop 0
	v_pk_mul_f32 v[94:95], v[96:97], v[94:95]
	s_nop 0
	v_pk_mul_f32 v[92:93], v[92:93], v[94:95]
	s_nop 0
	v_cvt_pk_bf16_f32 v91, v92, v93
	global_store_dwordx2 v[98:99], v[90:91], off
	v_mul_f32_e32 v90, 0xbfb8aa3b, v86
	v_mul_f32_e32 v91, 0xbfb8aa3b, v87
	v_exp_f32_e32 v90, v90
	v_exp_f32_e32 v91, v91
	v_add_f32_e32 v90, 1.0, v90
	v_add_f32_e32 v91, 1.0, v91
	v_rcp_f32_e32 v90, v90
	v_rcp_f32_e32 v91, v91
	s_nop 0
	v_pk_mul_f32 v[86:87], v[86:87], v[90:91]
	s_nop 0
	v_pk_mul_f32 v[82:83], v[82:83], v[86:87]
	s_nop 0
	v_cvt_pk_bf16_f32 v82, v82, v83
	v_mul_f32_e32 v83, 0xbfb8aa3b, v88
	v_exp_f32_e32 v83, v83
	s_nop 0
	v_add_f32_e32 v83, 1.0, v83
	v_rcp_f32_e32 v86, v83
	v_mul_f32_e32 v83, 0xbfb8aa3b, v89
	v_exp_f32_e32 v83, v83
	s_nop 0
	v_add_f32_e32 v83, 1.0, v83
	v_rcp_f32_e32 v87, v83
	s_nop 0
	v_pk_mul_f32 v[86:87], v[88:89], v[86:87]
	s_nop 0
	v_pk_mul_f32 v[84:85], v[84:85], v[86:87]
	s_nop 0
	v_cvt_pk_bf16_f32 v83, v84, v85
	global_store_dwordx2 v[98:99], v[82:83], off offset:128
	v_or_b32_e32 v82, 48, v144
	v_ashrrev_i32_e32 v83, 31, v82
	v_lshlrev_b64 v[84:85], 6, v[82:83]
	v_lshl_add_u64 v[96:97], s[4:5], 0, v[84:85]
	s_nop 0
	v_add_u32_e32 v225, 0x2000, v224
	global_load_dwordx4 v[192:195], v225, s[4:5]
	global_load_dwordx4 v[196:199], v225, s[4:5] offset:16
	global_load_dwordx4 v[200:203], v225, s[4:5] offset:32
	global_load_dwordx4 v[204:207], v225, s[4:5] offset:48
	s_waitcnt vmcnt(4)
; #define GAS __attribute__((address_space(1)))
; __device__ __forceinline__ unsigned cvt_pk_bf16(float lo, float hi) { f32x2 v = {lo, hi}; bf16x2_t b = __builtin_convertvector(v, bf16x2_t); return __builtin_bit_cast(unsigned, b); }
; __device__ __forceinline__ float sigmoid_f(float x) { return __builtin_amdgcn_rcpf(1.0f + __builtin_amdgcn_exp2f(-x * LOG2E)); }
; __device__ __forceinline__ float row_rs(const GAS float* rowss, int row) {
;     const GAS f32x4* p = (const GAS f32x4*)(rowss + (size_t)row * 16); const f32x4 a = p[0], b = p[1], c = p[2], d = p[3];
;     const float s = ((a[0] + a[1]) + (a[2] + a[3])) + ((b[0] + b[1]) + (b[2] + b[3])) + ((c[0] + c[1]) + (c[2] + c[3])) + ((d[0] + d[1]) + (d[2] + d[3]));
;     return __builtin_amdgcn_rsqf(s * (1.0f / 1024.0f) + 1e-6f);
;     __device__ __forceinline__ void operator()(const f32x4 (&acc)[2][2][4][2], const Unit& u, int wr, int wc, int fr, int fq) const {
;     ...
;             for (int m = 0; m < 4; ++m) { const int row = row0 + ai * HALF + m * 16; const float rs = row_rs(rowss, row); GAS bf16_t* rowp = H + (size_t)row * 2816 + col0;
; #pragma unroll
;                 for (int bj = 0; bj < 2; ++bj) { const f32x4 g = acc[ai][bj][m][0] * rs, uu = acc[ai][bj][m][1] * rs;
;                     u32x2 w; w.x = cvt_pk_bf16(g[0] * sigmoid_f(g[0]) * uu[0], g[1] * sigmoid_f(g[1]) * uu[1]); w.y = cvt_pk_bf16(g[2] * sigmoid_f(g[2]) * uu[2], g[3] * sigmoid_f(g[3]) * uu[3]);
;                     *(GAS u32x2*)(rowp + bj * (HALF / 2)) = w; } }
	v_add_f32_e32 v226, v208, v209
	v_add_f32_e32 v227, v210, v211
	v_add_f32_e32 v228, v226, v227
	v_add_f32_e32 v226, v212, v213
	v_add_f32_e32 v227, v214, v215
	v_add_f32_e32 v229, v226, v227
	v_add_f32_e32 v228, v228, v229
	v_add_f32_e32 v226, v216, v217
	v_add_f32_e32 v227, v218, v219
	v_add_f32_e32 v229, v226, v227
	v_add_f32_e32 v228, v228, v229
	v_add_f32_e32 v226, v220, v221
	v_add_f32_e32 v227, v222, v223
	v_add_f32_e32 v229, v226, v227
	v_add_f32_e32 v228, v228, v229
	v_mov_b32_e32 v83, v228
	v_fmamk_f32 v83, v83, 0x3a800000, v234
	v_rsq_f32_e32 v84, v83
	v_mad_i64_i32 v[82:83], s[18:19], v82, s11, v[140:141]
	v_lshl_add_u64 v[82:83], v[82:83], 0, v[142:143]
	v_pk_mul_f32 v[78:79], v[78:79], v[84:85] op_sel_hi:[1,0]
	v_pk_mul_f32 v[80:81], v[80:81], v[84:85] op_sel_hi:[1,0]
	v_pk_mul_f32 v[76:77], v[76:77], v[84:85] op_sel_hi:[1,0]
	v_pk_mul_f32 v[74:75], v[74:75], v[84:85] op_sel_hi:[1,0]
	v_mul_f32_e32 v85, 0xbfb8aa3b, v78
	v_exp_f32_e32 v85, v85
	s_nop 0
	v_add_f32_e32 v85, 1.0, v85
	v_rcp_f32_e32 v86, v85
	v_mul_f32_e32 v85, 0xbfb8aa3b, v79
	v_exp_f32_e32 v85, v85
	s_nop 0
	v_add_f32_e32 v85, 1.0, v85
	v_rcp_f32_e32 v87, v85
	v_pk_mul_f32 v[70:71], v[70:71], v[84:85] op_sel_hi:[1,0]
	v_pk_mul_f32 v[66:67], v[66:67], v[84:85] op_sel_hi:[1,0]
	v_pk_mul_f32 v[72:73], v[72:73], v[84:85] op_sel_hi:[1,0]
	v_pk_mul_f32 v[78:79], v[78:79], v[86:87]
	v_pk_mul_f32 v[68:69], v[68:69], v[84:85] op_sel_hi:[1,0]
	v_pk_mul_f32 v[74:75], v[74:75], v[78:79]
	s_nop 0
	v_cvt_pk_bf16_f32 v74, v74, v75
	v_mul_f32_e32 v75, 0xbfb8aa3b, v80
	v_exp_f32_e32 v75, v75
	s_nop 0
	v_add_f32_e32 v75, 1.0, v75
	v_rcp_f32_e32 v78, v75
	v_mul_f32_e32 v75, 0xbfb8aa3b, v81
	v_exp_f32_e32 v75, v75
	s_nop 0
	v_add_f32_e32 v75, 1.0, v75
	v_rcp_f32_e32 v79, v75
	s_nop 0
	v_pk_mul_f32 v[78:79], v[80:81], v[78:79]
	s_nop 0
	v_pk_mul_f32 v[76:77], v[76:77], v[78:79]
	s_nop 0
	v_cvt_pk_bf16_f32 v75, v76, v77
	global_store_dwordx2 v[82:83], v[74:75], off
	v_mul_f32_e32 v74, 0xbfb8aa3b, v70
	v_mul_f32_e32 v75, 0xbfb8aa3b, v71
	v_exp_f32_e32 v74, v74
	v_exp_f32_e32 v75, v75
	v_add_f32_e32 v74, 1.0, v74
	v_add_f32_e32 v75, 1.0, v75
	v_rcp_f32_e32 v74, v74
	v_rcp_f32_e32 v75, v75
	s_nop 0
	v_pk_mul_f32 v[70:71], v[70:71], v[74:75]
	s_nop 0
	v_pk_mul_f32 v[66:67], v[66:67], v[70:71]
	s_nop 0
	v_cvt_pk_bf16_f32 v66, v66, v67
	v_mul_f32_e32 v67, 0xbfb8aa3b, v72
	v_exp_f32_e32 v67, v67
	s_nop 0
	v_add_f32_e32 v67, 1.0, v67
	v_rcp_f32_e32 v70, v67
	v_mul_f32_e32 v67, 0xbfb8aa3b, v73
	v_exp_f32_e32 v67, v67
	s_nop 0
	v_add_f32_e32 v67, 1.0, v67
	v_rcp_f32_e32 v71, v67
	s_nop 0
	v_pk_mul_f32 v[70:71], v[72:73], v[70:71]
	s_nop 0
	v_pk_mul_f32 v[68:69], v[68:69], v[70:71]
	s_nop 0
	v_cvt_pk_bf16_f32 v67, v68, v69
	global_store_dwordx2 v[82:83], v[66:67], off offset:128
	v_add_u32_e32 v66, 0x80, v144
	v_ashrrev_i32_e32 v67, 31, v66
	v_lshlrev_b64 v[68:69], 6, v[66:67]
	v_lshl_add_u64 v[80:81], s[4:5], 0, v[68:69]
	s_nop 0
	v_add_u32_e32 v225, 0x2400, v224
	global_load_dwordx4 v[208:211], v225, s[4:5]
	global_load_dwordx4 v[212:215], v225, s[4:5] offset:16
	global_load_dwordx4 v[216:219], v225, s[4:5] offset:32
	global_load_dwordx4 v[220:223], v225, s[4:5] offset:48
	s_waitcnt vmcnt(4)
	v_add_f32_e32 v226, v192, v193
	v_add_f32_e32 v227, v194, v195
	v_add_f32_e32 v228, v226, v227
	v_add_f32_e32 v226, v196, v197
	v_add_f32_e32 v227, v198, v199
	v_add_f32_e32 v229, v226, v227
	v_add_f32_e32 v228, v228, v229
	v_add_f32_e32 v226, v200, v201
	v_add_f32_e32 v227, v202, v203
	v_add_f32_e32 v229, v226, v227
	v_add_f32_e32 v228, v228, v229
	v_add_f32_e32 v226, v204, v205
	v_add_f32_e32 v227, v206, v207
	v_add_f32_e32 v229, v226, v227
	v_add_f32_e32 v228, v228, v229
	v_mov_b32_e32 v67, v228
	v_fmamk_f32 v67, v67, 0x3a800000, v234
	v_rsq_f32_e32 v68, v67
	v_mad_i64_i32 v[66:67], s[18:19], v66, s11, v[140:141]
	v_lshl_add_u64 v[66:67], v[66:67], 0, v[142:143]
	v_pk_mul_f32 v[62:63], v[62:63], v[68:69] op_sel_hi:[1,0]
	v_pk_mul_f32 v[64:65], v[64:65], v[68:69] op_sel_hi:[1,0]
	v_pk_mul_f32 v[60:61], v[60:61], v[68:69] op_sel_hi:[1,0]
	v_pk_mul_f32 v[58:59], v[58:59], v[68:69] op_sel_hi:[1,0]
	v_mul_f32_e32 v69, 0xbfb8aa3b, v62
	v_exp_f32_e32 v69, v69
	s_nop 0
	v_add_f32_e32 v69, 1.0, v69
	v_rcp_f32_e32 v70, v69
	v_mul_f32_e32 v69, 0xbfb8aa3b, v63
	v_exp_f32_e32 v69, v69
	s_nop 0
	v_add_f32_e32 v69, 1.0, v69
	v_rcp_f32_e32 v71, v69
	v_pk_mul_f32 v[54:55], v[54:55], v[68:69] op_sel_hi:[1,0]
	v_pk_mul_f32 v[50:51], v[50:51], v[68:69] op_sel_hi:[1,0]
	v_pk_mul_f32 v[56:57], v[56:57], v[68:69] op_sel_hi:[1,0]
	v_pk_mul_f32 v[62:63], v[62:63], v[70:71]
	v_pk_mul_f32 v[52:53], v[52:53], v[68:69] op_sel_hi:[1,0]
	v_pk_mul_f32 v[58:59], v[58:59], v[62:63]
	s_nop 0
	v_cvt_pk_bf16_f32 v58, v58, v59
	v_mul_f32_e32 v59, 0xbfb8aa3b, v64
	v_exp_f32_e32 v59, v59
	s_nop 0
	v_add_f32_e32 v59, 1.0, v59
	v_rcp_f32_e32 v62, v59
	v_mul_f32_e32 v59, 0xbfb8aa3b, v65
	v_exp_f32_e32 v59, v59
	s_nop 0
	v_add_f32_e32 v59, 1.0, v59
	v_rcp_f32_e32 v63, v59
	s_nop 0
	v_pk_mul_f32 v[62:63], v[64:65], v[62:63]
	s_nop 0
	v_pk_mul_f32 v[60:61], v[60:61], v[62:63]
	s_nop 0
	v_cvt_pk_bf16_f32 v59, v60, v61
	global_store_dwordx2 v[66:67], v[58:59], off
	v_mul_f32_e32 v58, 0xbfb8aa3b, v54
	v_mul_f32_e32 v59, 0xbfb8aa3b, v55
	v_exp_f32_e32 v58, v58
	v_exp_f32_e32 v59, v59
	v_add_f32_e32 v58, 1.0, v58
	v_add_f32_e32 v59, 1.0, v59
	v_rcp_f32_e32 v58, v58
	v_rcp_f32_e32 v59, v59
	s_nop 0
	v_pk_mul_f32 v[54:55], v[54:55], v[58:59]
	s_nop 0
	v_pk_mul_f32 v[50:51], v[50:51], v[54:55]
	s_nop 0
	v_cvt_pk_bf16_f32 v50, v50, v51
	v_mul_f32_e32 v51, 0xbfb8aa3b, v56
	v_exp_f32_e32 v51, v51
	s_nop 0
	v_add_f32_e32 v51, 1.0, v51
	v_rcp_f32_e32 v54, v51
	v_mul_f32_e32 v51, 0xbfb8aa3b, v57
	v_exp_f32_e32 v51, v51
	s_nop 0
	v_add_f32_e32 v51, 1.0, v51
	v_rcp_f32_e32 v55, v51
	s_nop 0
	v_pk_mul_f32 v[54:55], v[56:57], v[54:55]
	s_nop 0
	v_pk_mul_f32 v[52:53], v[52:53], v[54:55]
	s_nop 0
	v_cvt_pk_bf16_f32 v51, v52, v53
	global_store_dwordx2 v[66:67], v[50:51], off offset:128
	v_add_u32_e32 v50, 0x90, v144
	v_ashrrev_i32_e32 v51, 31, v50
	v_lshlrev_b64 v[52:53], 6, v[50:51]
	v_lshl_add_u64 v[64:65], s[4:5], 0, v[52:53]
	s_nop 0
	v_add_u32_e32 v225, 0x2800, v224
	global_load_dwordx4 v[192:195], v225, s[4:5]
	global_load_dwordx4 v[196:199], v225, s[4:5] offset:16
	global_load_dwordx4 v[200:203], v225, s[4:5] offset:32
	global_load_dwordx4 v[204:207], v225, s[4:5] offset:48
	s_waitcnt vmcnt(4)
; #define GAS __attribute__((address_space(1)))
; __device__ __forceinline__ unsigned cvt_pk_bf16(float lo, float hi) { f32x2 v = {lo, hi}; bf16x2_t b = __builtin_convertvector(v, bf16x2_t); return __builtin_bit_cast(unsigned, b); }
; __device__ __forceinline__ float sigmoid_f(float x) { return __builtin_amdgcn_rcpf(1.0f + __builtin_amdgcn_exp2f(-x * LOG2E)); }
; __device__ __forceinline__ float row_rs(const GAS float* rowss, int row) {
;     const GAS f32x4* p = (const GAS f32x4*)(rowss + (size_t)row * 16); const f32x4 a = p[0], b = p[1], c = p[2], d = p[3];
;     const float s = ((a[0] + a[1]) + (a[2] + a[3])) + ((b[0] + b[1]) + (b[2] + b[3])) + ((c[0] + c[1]) + (c[2] + c[3])) + ((d[0] + d[1]) + (d[2] + d[3]));
;     return __builtin_amdgcn_rsqf(s * (1.0f / 1024.0f) + 1e-6f);
;     __device__ __forceinline__ void operator()(const f32x4 (&acc)[2][2][4][2], const Unit& u, int wr, int wc, int fr, int fq) const {
;     ...
;             for (int m = 0; m < 4; ++m) { const int row = row0 + ai * HALF + m * 16; const float rs = row_rs(rowss, row); GAS bf16_t* rowp = H + (size_t)row * 2816 + col0;
; #pragma unroll
;                 for (int bj = 0; bj < 2; ++bj) { const f32x4 g = acc[ai][bj][m][0] * rs, uu = acc[ai][bj][m][1] * rs;
;                     u32x2 w; w.x = cvt_pk_bf16(g[0] * sigmoid_f(g[0]) * uu[0], g[1] * sigmoid_f(g[1]) * uu[1]); w.y = cvt_pk_bf16(g[2] * sigmoid_f(g[2]) * uu[2], g[3] * sigmoid_f(g[3]) * uu[3]);
;                     *(GAS u32x2*)(rowp + bj * (HALF / 2)) = w; } }
	v_add_f32_e32 v226, v208, v209
	v_add_f32_e32 v227, v210, v211
	v_add_f32_e32 v228, v226, v227
	v_add_f32_e32 v226, v212, v213
	v_add_f32_e32 v227, v214, v215
	v_add_f32_e32 v229, v226, v227
	v_add_f32_e32 v228, v228, v229
	v_add_f32_e32 v226, v216, v217
	v_add_f32_e32 v227, v218, v219
	v_add_f32_e32 v229, v226, v227
	v_add_f32_e32 v228, v228, v229
	v_add_f32_e32 v226, v220, v221
	v_add_f32_e32 v227, v222, v223
	v_add_f32_e32 v229, v226, v227
	v_add_f32_e32 v228, v228, v229
	v_mov_b32_e32 v51, v228
	v_fmamk_f32 v51, v51, 0x3a800000, v234
	v_rsq_f32_e32 v52, v51
	v_mad_i64_i32 v[50:51], s[18:19], v50, s11, v[140:141]
	v_lshl_add_u64 v[50:51], v[50:51], 0, v[142:143]
	v_pk_mul_f32 v[46:47], v[46:47], v[52:53] op_sel_hi:[1,0]
	v_pk_mul_f32 v[48:49], v[48:49], v[52:53] op_sel_hi:[1,0]
	v_pk_mul_f32 v[44:45], v[44:45], v[52:53] op_sel_hi:[1,0]
	v_pk_mul_f32 v[42:43], v[42:43], v[52:53] op_sel_hi:[1,0]
	v_mul_f32_e32 v53, 0xbfb8aa3b, v46
	v_exp_f32_e32 v53, v53
	s_nop 0
	v_add_f32_e32 v53, 1.0, v53
	v_rcp_f32_e32 v54, v53
	v_mul_f32_e32 v53, 0xbfb8aa3b, v47
	v_exp_f32_e32 v53, v53
	s_nop 0
	v_add_f32_e32 v53, 1.0, v53
	v_rcp_f32_e32 v55, v53
	v_pk_mul_f32 v[38:39], v[38:39], v[52:53] op_sel_hi:[1,0]
	v_pk_mul_f32 v[34:35], v[34:35], v[52:53] op_sel_hi:[1,0]
	v_pk_mul_f32 v[40:41], v[40:41], v[52:53] op_sel_hi:[1,0]
	v_pk_mul_f32 v[46:47], v[46:47], v[54:55]
	v_pk_mul_f32 v[36:37], v[36:37], v[52:53] op_sel_hi:[1,0]
	v_pk_mul_f32 v[42:43], v[42:43], v[46:47]
	s_nop 0
	v_cvt_pk_bf16_f32 v42, v42, v43
	v_mul_f32_e32 v43, 0xbfb8aa3b, v48
	v_exp_f32_e32 v43, v43
	s_nop 0
	v_add_f32_e32 v43, 1.0, v43
	v_rcp_f32_e32 v46, v43
	v_mul_f32_e32 v43, 0xbfb8aa3b, v49
	v_exp_f32_e32 v43, v43
	s_nop 0
	v_add_f32_e32 v43, 1.0, v43
	v_rcp_f32_e32 v47, v43
	s_nop 0
	v_pk_mul_f32 v[46:47], v[48:49], v[46:47]
	s_nop 0
	v_pk_mul_f32 v[44:45], v[44:45], v[46:47]
	s_nop 0
	v_cvt_pk_bf16_f32 v43, v44, v45
	global_store_dwordx2 v[50:51], v[42:43], off
	v_mul_f32_e32 v42, 0xbfb8aa3b, v38
	v_mul_f32_e32 v43, 0xbfb8aa3b, v39
	v_exp_f32_e32 v42, v42
	v_exp_f32_e32 v43, v43
	v_add_f32_e32 v42, 1.0, v42
	v_add_f32_e32 v43, 1.0, v43
	v_rcp_f32_e32 v42, v42
	v_rcp_f32_e32 v43, v43
	s_nop 0
	v_pk_mul_f32 v[38:39], v[38:39], v[42:43]
	s_nop 0
	v_pk_mul_f32 v[34:35], v[34:35], v[38:39]
	s_nop 0
	v_cvt_pk_bf16_f32 v34, v34, v35
	v_mul_f32_e32 v35, 0xbfb8aa3b, v40
	v_exp_f32_e32 v35, v35
	s_nop 0
	v_add_f32_e32 v35, 1.0, v35
	v_rcp_f32_e32 v38, v35
	v_mul_f32_e32 v35, 0xbfb8aa3b, v41
	v_exp_f32_e32 v35, v35
	s_nop 0
	v_add_f32_e32 v35, 1.0, v35
	v_rcp_f32_e32 v39, v35
	s_nop 0
	v_pk_mul_f32 v[38:39], v[40:41], v[38:39]
	s_nop 0
	v_pk_mul_f32 v[36:37], v[36:37], v[38:39]
	s_nop 0
	v_cvt_pk_bf16_f32 v35, v36, v37
	global_store_dwordx2 v[50:51], v[34:35], off offset:128
	v_add_u32_e32 v34, 0xa0, v144
	v_ashrrev_i32_e32 v35, 31, v34
	v_lshlrev_b64 v[36:37], 6, v[34:35]
	v_lshl_add_u64 v[48:49], s[4:5], 0, v[36:37]
	s_nop 0
	v_add_u32_e32 v225, 0x2c00, v224
	global_load_dwordx4 v[208:211], v225, s[4:5]
	global_load_dwordx4 v[212:215], v225, s[4:5] offset:16
	global_load_dwordx4 v[216:219], v225, s[4:5] offset:32
	global_load_dwordx4 v[220:223], v225, s[4:5] offset:48
	s_waitcnt vmcnt(4)
; #define GAS __attribute__((address_space(1)))
; __device__ __forceinline__ unsigned cvt_pk_bf16(float lo, float hi) { f32x2 v = {lo, hi}; bf16x2_t b = __builtin_convertvector(v, bf16x2_t); return __builtin_bit_cast(unsigned, b); }
; __device__ __forceinline__ float sigmoid_f(float x) { return __builtin_amdgcn_rcpf(1.0f + __builtin_amdgcn_exp2f(-x * LOG2E)); }
; __device__ __forceinline__ float row_rs(const GAS float* rowss, int row) {
;     const GAS f32x4* p = (const GAS f32x4*)(rowss + (size_t)row * 16); const f32x4 a = p[0], b = p[1], c = p[2], d = p[3];
;     const float s = ((a[0] + a[1]) + (a[2] + a[3])) + ((b[0] + b[1]) + (b[2] + b[3])) + ((c[0] + c[1]) + (c[2] + c[3])) + ((d[0] + d[1]) + (d[2] + d[3]));
;     return __builtin_amdgcn_rsqf(s * (1.0f / 1024.0f) + 1e-6f);
;     __device__ __forceinline__ void operator()(const f32x4 (&acc)[2][2][4][2], const Unit& u, int wr, int wc, int fr, int fq) const {
;     ...
;             for (int m = 0; m < 4; ++m) { const int row = row0 + ai * HALF + m * 16; const float rs = row_rs(rowss, row); GAS bf16_t* rowp = H + (size_t)row * 2816 + col0;
; #pragma unroll
;                 for (int bj = 0; bj < 2; ++bj) { const f32x4 g = acc[ai][bj][m][0] * rs, uu = acc[ai][bj][m][1] * rs;
;                     u32x2 w; w.x = cvt_pk_bf16(g[0] * sigmoid_f(g[0]) * uu[0], g[1] * sigmoid_f(g[1]) * uu[1]); w.y = cvt_pk_bf16(g[2] * sigmoid_f(g[2]) * uu[2], g[3] * sigmoid_f(g[3]) * uu[3]);
;                     *(GAS u32x2*)(rowp + bj * (HALF / 2)) = w; } }
	v_add_f32_e32 v226, v192, v193
	v_add_f32_e32 v227, v194, v195
	v_add_f32_e32 v228, v226, v227
	v_add_f32_e32 v226, v196, v197
	v_add_f32_e32 v227, v198, v199
	v_add_f32_e32 v229, v226, v227
	v_add_f32_e32 v228, v228, v229
	v_add_f32_e32 v226, v200, v201
	v_add_f32_e32 v227, v202, v203
	v_add_f32_e32 v229, v226, v227
	v_add_f32_e32 v228, v228, v229
	v_add_f32_e32 v226, v204, v205
	v_add_f32_e32 v227, v206, v207
	v_add_f32_e32 v229, v226, v227
	v_add_f32_e32 v228, v228, v229
	v_mov_b32_e32 v35, v228
	v_fmamk_f32 v35, v35, 0x3a800000, v234
	v_rsq_f32_e32 v36, v35
	v_mad_i64_i32 v[34:35], s[18:19], v34, s11, v[140:141]
	v_lshl_add_u64 v[34:35], v[34:35], 0, v[142:143]
	v_pk_mul_f32 v[30:31], v[30:31], v[36:37] op_sel_hi:[1,0]
	v_pk_mul_f32 v[32:33], v[32:33], v[36:37] op_sel_hi:[1,0]
	v_pk_mul_f32 v[28:29], v[28:29], v[36:37] op_sel_hi:[1,0]
	v_pk_mul_f32 v[26:27], v[26:27], v[36:37] op_sel_hi:[1,0]
	v_mul_f32_e32 v37, 0xbfb8aa3b, v30
	v_exp_f32_e32 v37, v37
	s_nop 0
	v_add_f32_e32 v37, 1.0, v37
	v_rcp_f32_e32 v38, v37
	v_mul_f32_e32 v37, 0xbfb8aa3b, v31
	v_exp_f32_e32 v37, v37
	s_nop 0
	v_add_f32_e32 v37, 1.0, v37
	v_rcp_f32_e32 v39, v37
	v_pk_mul_f32 v[22:23], v[22:23], v[36:37] op_sel_hi:[1,0]
	v_pk_mul_f32 v[18:19], v[18:19], v[36:37] op_sel_hi:[1,0]
	v_pk_mul_f32 v[24:25], v[24:25], v[36:37] op_sel_hi:[1,0]
	v_pk_mul_f32 v[30:31], v[30:31], v[38:39]
	v_pk_mul_f32 v[20:21], v[20:21], v[36:37] op_sel_hi:[1,0]
	v_pk_mul_f32 v[26:27], v[26:27], v[30:31]
	s_nop 0
	v_cvt_pk_bf16_f32 v26, v26, v27
	v_mul_f32_e32 v27, 0xbfb8aa3b, v32
	v_exp_f32_e32 v27, v27
	s_nop 0
	v_add_f32_e32 v27, 1.0, v27
	v_rcp_f32_e32 v30, v27
	v_mul_f32_e32 v27, 0xbfb8aa3b, v33
	v_exp_f32_e32 v27, v27
	s_nop 0
	v_add_f32_e32 v27, 1.0, v27
	v_rcp_f32_e32 v31, v27
	s_nop 0
	v_pk_mul_f32 v[30:31], v[32:33], v[30:31]
	s_nop 0
	v_pk_mul_f32 v[28:29], v[28:29], v[30:31]
	s_nop 0
	v_cvt_pk_bf16_f32 v27, v28, v29
	global_store_dwordx2 v[34:35], v[26:27], off
	v_mul_f32_e32 v26, 0xbfb8aa3b, v22
	v_mul_f32_e32 v27, 0xbfb8aa3b, v23
	v_exp_f32_e32 v26, v26
	v_exp_f32_e32 v27, v27
	v_add_f32_e32 v26, 1.0, v26
	v_add_f32_e32 v27, 1.0, v27
	v_rcp_f32_e32 v26, v26
	v_rcp_f32_e32 v27, v27
	s_nop 0
	v_pk_mul_f32 v[22:23], v[22:23], v[26:27]
	s_nop 0
	v_pk_mul_f32 v[18:19], v[18:19], v[22:23]
	s_nop 0
	v_cvt_pk_bf16_f32 v18, v18, v19
	v_mul_f32_e32 v19, 0xbfb8aa3b, v24
	v_exp_f32_e32 v19, v19
	s_nop 0
	v_add_f32_e32 v19, 1.0, v19
	v_rcp_f32_e32 v22, v19
	v_mul_f32_e32 v19, 0xbfb8aa3b, v25
	v_exp_f32_e32 v19, v19
	s_nop 0
	v_add_f32_e32 v19, 1.0, v19
	v_rcp_f32_e32 v23, v19
	s_nop 0
	v_pk_mul_f32 v[22:23], v[24:25], v[22:23]
	s_nop 0
	v_pk_mul_f32 v[20:21], v[20:21], v[22:23]
	s_nop 0
	v_cvt_pk_bf16_f32 v19, v20, v21
	global_store_dwordx2 v[34:35], v[18:19], off offset:128
	v_add_u32_e32 v18, 0xb0, v144
	v_ashrrev_i32_e32 v19, 31, v18
	v_lshlrev_b64 v[20:21], 6, v[18:19]
	v_lshl_add_u64 v[32:33], s[4:5], 0, v[20:21]
	s_nop 0
	s_waitcnt vmcnt(0)
	v_add_f32_e32 v226, v208, v209
	v_add_f32_e32 v227, v210, v211
	v_add_f32_e32 v228, v226, v227
	v_add_f32_e32 v226, v212, v213
	v_add_f32_e32 v227, v214, v215
	v_add_f32_e32 v229, v226, v227
	v_add_f32_e32 v228, v228, v229
	v_add_f32_e32 v226, v216, v217
	v_add_f32_e32 v227, v218, v219
	v_add_f32_e32 v229, v226, v227
	v_add_f32_e32 v228, v228, v229
	v_add_f32_e32 v226, v220, v221
	v_add_f32_e32 v227, v222, v223
	v_add_f32_e32 v229, v226, v227
	v_add_f32_e32 v228, v228, v229
	v_mov_b32_e32 v19, v228
	v_fmamk_f32 v19, v19, 0x3a800000, v234
	v_rsq_f32_e32 v20, v19
	v_mad_i64_i32 v[18:19], s[18:19], v18, s11, v[140:141]
	v_lshl_add_u64 v[18:19], v[18:19], 0, v[142:143]
	v_pk_mul_f32 v[14:15], v[14:15], v[20:21] op_sel_hi:[1,0]
	v_pk_mul_f32 v[16:17], v[16:17], v[20:21] op_sel_hi:[1,0]
	v_pk_mul_f32 v[12:13], v[12:13], v[20:21] op_sel_hi:[1,0]
	v_pk_mul_f32 v[10:11], v[10:11], v[20:21] op_sel_hi:[1,0]
	v_mul_f32_e32 v21, 0xbfb8aa3b, v14
	v_exp_f32_e32 v21, v21
	s_mov_b64 s[18:19], -1
	v_add_f32_e32 v21, 1.0, v21
	v_rcp_f32_e32 v22, v21
	v_mul_f32_e32 v21, 0xbfb8aa3b, v15
	v_exp_f32_e32 v21, v21
	s_nop 0
	v_add_f32_e32 v21, 1.0, v21
	v_rcp_f32_e32 v23, v21
	v_pk_mul_f32 v[6:7], v[6:7], v[20:21] op_sel_hi:[1,0]
	v_pk_mul_f32 v[2:3], v[2:3], v[20:21] op_sel_hi:[1,0]
	v_pk_mul_f32 v[8:9], v[8:9], v[20:21] op_sel_hi:[1,0]
	v_pk_mul_f32 v[14:15], v[14:15], v[22:23]
	v_pk_mul_f32 v[4:5], v[4:5], v[20:21] op_sel_hi:[1,0]
	v_pk_mul_f32 v[10:11], v[10:11], v[14:15]
	s_nop 0
	v_cvt_pk_bf16_f32 v10, v10, v11
	v_mul_f32_e32 v11, 0xbfb8aa3b, v16
	v_exp_f32_e32 v11, v11
	s_nop 0
	v_add_f32_e32 v11, 1.0, v11
	v_rcp_f32_e32 v14, v11
	v_mul_f32_e32 v11, 0xbfb8aa3b, v17
	v_exp_f32_e32 v11, v11
	s_nop 0
	v_add_f32_e32 v11, 1.0, v11
	v_rcp_f32_e32 v15, v11
	s_nop 0
	v_pk_mul_f32 v[14:15], v[16:17], v[14:15]
	s_nop 0
	v_pk_mul_f32 v[12:13], v[12:13], v[14:15]
	s_nop 0
	v_cvt_pk_bf16_f32 v11, v12, v13
	global_store_dwordx2 v[18:19], v[10:11], off
	v_mul_f32_e32 v10, 0xbfb8aa3b, v6
	v_mul_f32_e32 v11, 0xbfb8aa3b, v7
	v_exp_f32_e32 v10, v10
	v_exp_f32_e32 v11, v11
	v_add_f32_e32 v10, 1.0, v10
	v_add_f32_e32 v11, 1.0, v11
	v_rcp_f32_e32 v10, v10
	v_rcp_f32_e32 v11, v11
	s_nop 0
	v_pk_mul_f32 v[6:7], v[6:7], v[10:11]
	s_nop 0
	v_pk_mul_f32 v[2:3], v[2:3], v[6:7]
	s_nop 0
	v_cvt_pk_bf16_f32 v2, v2, v3
	v_mul_f32_e32 v3, 0xbfb8aa3b, v8
	v_exp_f32_e32 v3, v3
	s_nop 0
	v_add_f32_e32 v3, 1.0, v3
	v_rcp_f32_e32 v6, v3
	v_mul_f32_e32 v3, 0xbfb8aa3b, v9
	v_exp_f32_e32 v3, v3
	s_nop 0
	v_add_f32_e32 v3, 1.0, v3
	v_rcp_f32_e32 v7, v3
	s_nop 0
	v_pk_mul_f32 v[6:7], v[8:9], v[6:7]
	s_nop 0
	v_pk_mul_f32 v[4:5], v[4:5], v[6:7]
	s_nop 0
	v_cvt_pk_bf16_f32 v3, v4, v5
	global_store_dwordx2 v[18:19], v[2:3], off offset:128
	s_cbranch_vccnz .LBB0_748
	s_andn2_b64 vcc, exec, s[0:1]
	s_cbranch_vccnz .LBB0_747
	s_barrier
	s_branch .LBB0_747
